# prep unit decode: unit index split by shift and mask (8 chunks per segment) instead of the generic integer division
# speedup vs baseline: 1.0008x; 1.0008x over previous
.Lps_j:
	v_mov_b32_e32 v0, s1
	s_mov_b64 s[0:1], -1
	s_cbranch_scc0 .LBB0_550
	v_lshl_add_u32 v0, v0, 1, v147
	v_readlane_b32 s0, v254, 33
	v_mov_b32_e32 v148, v156
	v_bfrev_b32_e32 v165, 1
	v_ashrrev_i32_e32 v162, 3, v0
	v_and_b32_e32 v161, 7, v0
	v_and_b32_e32 v164, 1, v162
	v_add_u32_e32 v2, s0, v161
	v_ashrrev_i32_e32 v0, 4, v162
	v_sub_u32_e32 v3, s36, v2
	v_cmp_eq_u32_e64 s[44:45], 0, v164
	v_readlane_b32 s0, v254, 31
	v_readlane_b32 s1, v254, 32
	v_cndmask_b32_e64 v2, v3, v2, s[44:45]
	v_lshl_add_u32 v3, v0, 8, v246
	v_lshlrev_b32_e32 v0, 12, v0
	v_cndmask_b32_e64 v26, v0, v3, s[0:1]
	v_bfe_u32 v163, v162, 1, 3
	v_ashrrev_i32_e32 v27, 31, v26
	v_lshlrev_b32_e32 v4, 6, v2
	v_lshrrev_b32_e32 v130, 6, v148
	v_cmp_eq_u32_e64 s[46:47], v130, v147
	v_lshl_or_b32 v130, v164, 3, v163
	v_lshlrev_b32_e32 v130, 2, v130
	s_nop 0
	v_readfirstlane_b32 s100, v130
	s_nop 4
	s_load_dword s101, s[82:83], s100
	s_load_dword s100, s[80:81], s100
	v_mov_b32_e32 v130, 0
	v_mov_b32_e32 v166, 0
	s_and_saveexec_b64 s[0:1], s[46:47]
	s_cbranch_execz .LBB0_558
	v_and_b32_e32 v2, 63, v148
	v_xor_b32_e32 v0, 63, v2
	v_ashrrev_i32_e32 v5, 31, v4
	v_cndmask_b32_e64 v0, v0, v2, s[44:45]
	v_lshl_add_u64 v[2:3], v[4:5], 0, v[26:27]
	v_or_b32_e32 v2, v2, v0
	v_readlane_b32 s22, v251, 58
	v_lshlrev_b64 v[2:3], 7, v[2:3]
	v_readlane_b32 s23, v251, 59
	v_lshlrev_b32_e32 v0, 5, v164
	s_nop 0
	v_lshl_add_u64 v[2:3], s[22:23], 0, v[2:3]
	v_lshl_add_u64 v[2:3], v[2:3], 0, v[0:1]
	v_lshlrev_b32_e32 v0, 2, v163
	v_lshl_add_u64 v[2:3], v[2:3], 0, v[0:1]
	global_load_dword v165, v[2:3], off
	global_load_dword v166, v[2:3], off offset:64
